# residual epilogue (DOWN/EVOUT/ODOUT) rewritten by hand: 16 XB tile loads issued up front, stores not waited, bpermutes batched
# speedup vs baseline: 1.0046x; 1.0046x over previous
.LBB0_1612:
	v_lshl_add_u32 v156, s41, 8, v160
	v_mov_b32_e32 v157, 0
	v_lshl_or_b32 v154, s33, 8, v162
	v_mov_b32_e32 v155, 0
	v_lshlrev_b64 v[158:159], 11, v[156:157]
	v_lshl_add_u64 v[158:159], s[70:71], 0, v[158:159]
	v_lshl_add_u64 v[158:159], v[154:155], 1, v[158:159]
	s_mov_b64 s[20:21], 0x8000
	s_mov_b64 s[0:1], 0x40000
	v_lshl_add_u64 v[174:175], v[158:159], 0, s[20:21]
	v_lshl_add_u64 v[180:181], v[158:159], 0, s[0:1]
	v_lshl_add_u64 v[176:177], v[174:175], 0, s[20:21]
	v_lshl_add_u64 v[182:183], v[180:181], 0, s[20:21]
	v_lshl_add_u64 v[178:179], v[176:177], 0, s[20:21]
	v_lshl_add_u64 v[252:253], v[182:183], 0, s[20:21]
	global_load_dwordx4 v[196:199], v[158:159], off
	global_load_dwordx4 v[200:203], v[158:159], off offset:256
	global_load_dwordx4 v[204:207], v[174:175], off
	global_load_dwordx4 v[208:211], v[174:175], off offset:256
	global_load_dwordx4 v[212:215], v[176:177], off
	global_load_dwordx4 v[216:219], v[176:177], off offset:256
	global_load_dwordx4 v[220:223], v[178:179], off
	global_load_dwordx4 v[224:227], v[178:179], off offset:256
	global_load_dwordx4 v[228:231], v[180:181], off
	global_load_dwordx4 v[232:235], v[180:181], off offset:256
	global_load_dwordx4 v[236:239], v[182:183], off
	global_load_dwordx4 v[240:243], v[182:183], off offset:256
	global_load_dwordx4 v[244:247], v[252:253], off
	global_load_dwordx4 v[248:251], v[252:253], off offset:256
	v_lshl_add_u64 v[154:155], v[252:253], 0, s[20:21]
	s_and_b64 vcc, exec, s[16:17]
	s_cbranch_vccz .LBB0_1614
	s_barrier
.LBB0_1614:
	s_waitcnt vmcnt(13)
	v_lshlrev_b32_e32 v164, 16, v196
	v_and_b32_e32 v165, 0xffff0000, v196
	v_lshlrev_b32_e32 v166, 16, v197
	v_and_b32_e32 v167, 0xffff0000, v197
	v_lshlrev_b32_e32 v168, 16, v198
	v_and_b32_e32 v169, 0xffff0000, v198
	v_lshlrev_b32_e32 v170, 16, v199
	v_and_b32_e32 v171, 0xffff0000, v199
	v_pk_fma_f32 v[122:123], v[148:149], v[122:123], v[164:165]
	v_pk_fma_f32 v[124:125], v[148:149], v[124:125], v[166:167]
	v_pk_fma_f32 v[126:127], v[148:149], v[126:127], v[168:169]
	v_pk_fma_f32 v[128:129], v[148:149], v[128:129], v[170:171]
	v_cvt_pk_bf16_f32 v196, v122, v123
	v_cvt_pk_bf16_f32 v197, v124, v125
	v_cvt_pk_bf16_f32 v198, v126, v127
	v_cvt_pk_bf16_f32 v199, v128, v129
	global_store_dwordx4 v[158:159], v[196:199], off nt
	v_lshlrev_b32_e32 v122, 16, v196
	v_and_b32_e32 v123, 0xffff0000, v196
	v_lshlrev_b32_e32 v124, 16, v197
	v_and_b32_e32 v125, 0xffff0000, v197
	v_lshlrev_b32_e32 v126, 16, v198
	v_and_b32_e32 v127, 0xffff0000, v198
	v_lshlrev_b32_e32 v128, 16, v199
	v_and_b32_e32 v129, 0xffff0000, v199
	v_mul_f32_e32 v172, v123, v123
	v_fmac_f32_e32 v172, v122, v122
	v_fmac_f32_e32 v172, v124, v124
	v_fmac_f32_e32 v172, v125, v125
	v_fmac_f32_e32 v172, v126, v126
	v_fmac_f32_e32 v172, v127, v127
	v_fmac_f32_e32 v172, v128, v128
	v_fmac_f32_e32 v172, v129, v129
	s_waitcnt vmcnt(13)
	v_lshlrev_b32_e32 v164, 16, v200
	v_and_b32_e32 v165, 0xffff0000, v200
	v_lshlrev_b32_e32 v166, 16, v201
	v_and_b32_e32 v167, 0xffff0000, v201
	v_lshlrev_b32_e32 v168, 16, v202
	v_and_b32_e32 v169, 0xffff0000, v202
	v_lshlrev_b32_e32 v170, 16, v203
	v_and_b32_e32 v171, 0xffff0000, v203
	v_pk_fma_f32 v[118:119], v[148:149], v[118:119], v[164:165]
	v_pk_fma_f32 v[120:121], v[148:149], v[120:121], v[166:167]
	v_pk_fma_f32 v[114:115], v[148:149], v[114:115], v[168:169]
	v_pk_fma_f32 v[116:117], v[148:149], v[116:117], v[170:171]
	v_cvt_pk_bf16_f32 v200, v118, v119
	v_cvt_pk_bf16_f32 v201, v120, v121
	v_cvt_pk_bf16_f32 v202, v114, v115
	v_cvt_pk_bf16_f32 v203, v116, v117
	global_store_dwordx4 v[158:159], v[200:203], off offset:256 nt
	v_lshlrev_b32_e32 v118, 16, v200
	v_and_b32_e32 v119, 0xffff0000, v200
	v_lshlrev_b32_e32 v120, 16, v201
	v_and_b32_e32 v121, 0xffff0000, v201
	v_lshlrev_b32_e32 v114, 16, v202
	v_and_b32_e32 v115, 0xffff0000, v202
	v_lshlrev_b32_e32 v116, 16, v203
	v_and_b32_e32 v117, 0xffff0000, v203
	v_fmac_f32_e32 v172, v118, v118
	v_fmac_f32_e32 v172, v119, v119
	v_fmac_f32_e32 v172, v120, v120
	v_fmac_f32_e32 v172, v121, v121
	v_fmac_f32_e32 v172, v114, v114
	v_fmac_f32_e32 v172, v115, v115
	v_fmac_f32_e32 v172, v116, v116
	v_fmac_f32_e32 v172, v117, v117
	global_load_dwordx4 v[114:117], v[154:155], off
	global_load_dwordx4 v[118:121], v[154:155], off offset:256
	s_waitcnt vmcnt(15)
	v_lshlrev_b32_e32 v164, 16, v204
	v_and_b32_e32 v165, 0xffff0000, v204
	v_lshlrev_b32_e32 v166, 16, v205
	v_and_b32_e32 v167, 0xffff0000, v205
	v_lshlrev_b32_e32 v168, 16, v206
	v_and_b32_e32 v169, 0xffff0000, v206
	v_lshlrev_b32_e32 v170, 16, v207
	v_and_b32_e32 v171, 0xffff0000, v207
	v_pk_fma_f32 v[110:111], v[148:149], v[110:111], v[164:165]
	v_pk_fma_f32 v[112:113], v[148:149], v[112:113], v[166:167]
	v_pk_fma_f32 v[106:107], v[148:149], v[106:107], v[168:169]
	v_pk_fma_f32 v[108:109], v[148:149], v[108:109], v[170:171]
	v_cvt_pk_bf16_f32 v204, v110, v111
	v_cvt_pk_bf16_f32 v205, v112, v113
	v_cvt_pk_bf16_f32 v206, v106, v107
	v_cvt_pk_bf16_f32 v207, v108, v109
	global_store_dwordx4 v[174:175], v[204:207], off nt
	v_lshlrev_b32_e32 v110, 16, v204
	v_and_b32_e32 v111, 0xffff0000, v204
	v_lshlrev_b32_e32 v112, 16, v205
	v_and_b32_e32 v113, 0xffff0000, v205
	v_lshlrev_b32_e32 v106, 16, v206
	v_and_b32_e32 v107, 0xffff0000, v206
	v_lshlrev_b32_e32 v108, 16, v207
	v_and_b32_e32 v109, 0xffff0000, v207
	v_mul_f32_e32 v122, v111, v111
	v_fmac_f32_e32 v122, v110, v110
	v_fmac_f32_e32 v122, v112, v112
	v_fmac_f32_e32 v122, v113, v113
	v_fmac_f32_e32 v122, v106, v106
	v_fmac_f32_e32 v122, v107, v107
	v_fmac_f32_e32 v122, v108, v108
	v_fmac_f32_e32 v122, v109, v109
	s_waitcnt vmcnt(15)
	v_lshlrev_b32_e32 v164, 16, v208
	v_and_b32_e32 v165, 0xffff0000, v208
	v_lshlrev_b32_e32 v166, 16, v209
	v_and_b32_e32 v167, 0xffff0000, v209
	v_lshlrev_b32_e32 v168, 16, v210
	v_and_b32_e32 v169, 0xffff0000, v210
	v_lshlrev_b32_e32 v170, 16, v211
	v_and_b32_e32 v171, 0xffff0000, v211
	v_pk_fma_f32 v[102:103], v[148:149], v[102:103], v[164:165]
	v_pk_fma_f32 v[104:105], v[148:149], v[104:105], v[166:167]
	v_pk_fma_f32 v[98:99], v[148:149], v[98:99], v[168:169]
	v_pk_fma_f32 v[100:101], v[148:149], v[100:101], v[170:171]
	v_cvt_pk_bf16_f32 v208, v102, v103
	v_cvt_pk_bf16_f32 v209, v104, v105
	v_cvt_pk_bf16_f32 v210, v98, v99
	v_cvt_pk_bf16_f32 v211, v100, v101
	global_store_dwordx4 v[174:175], v[208:211], off offset:256 nt
	v_lshlrev_b32_e32 v102, 16, v208
	v_and_b32_e32 v103, 0xffff0000, v208
	v_lshlrev_b32_e32 v104, 16, v209
	v_and_b32_e32 v105, 0xffff0000, v209
	v_lshlrev_b32_e32 v98, 16, v210
	v_and_b32_e32 v99, 0xffff0000, v210
	v_lshlrev_b32_e32 v100, 16, v211
	v_and_b32_e32 v101, 0xffff0000, v211
	v_fmac_f32_e32 v122, v102, v102
	v_fmac_f32_e32 v122, v103, v103
	v_fmac_f32_e32 v122, v104, v104
	v_fmac_f32_e32 v122, v105, v105
	v_fmac_f32_e32 v122, v98, v98
	v_fmac_f32_e32 v122, v99, v99
	v_fmac_f32_e32 v122, v100, v100
	v_fmac_f32_e32 v122, v101, v101
	s_waitcnt vmcnt(15)
	v_lshlrev_b32_e32 v164, 16, v212
	v_and_b32_e32 v165, 0xffff0000, v212
	v_lshlrev_b32_e32 v166, 16, v213
	v_and_b32_e32 v167, 0xffff0000, v213
	v_lshlrev_b32_e32 v168, 16, v214
	v_and_b32_e32 v169, 0xffff0000, v214
	v_lshlrev_b32_e32 v170, 16, v215
	v_and_b32_e32 v171, 0xffff0000, v215
	v_pk_fma_f32 v[94:95], v[148:149], v[94:95], v[164:165]
	v_pk_fma_f32 v[96:97], v[148:149], v[96:97], v[166:167]
	v_pk_fma_f32 v[90:91], v[148:149], v[90:91], v[168:169]
	v_pk_fma_f32 v[92:93], v[148:149], v[92:93], v[170:171]
	v_cvt_pk_bf16_f32 v212, v94, v95
	v_cvt_pk_bf16_f32 v213, v96, v97
	v_cvt_pk_bf16_f32 v214, v90, v91
	v_cvt_pk_bf16_f32 v215, v92, v93
	global_store_dwordx4 v[176:177], v[212:215], off nt
	v_lshlrev_b32_e32 v94, 16, v212
	v_and_b32_e32 v95, 0xffff0000, v212
	v_lshlrev_b32_e32 v96, 16, v213
	v_and_b32_e32 v97, 0xffff0000, v213
	v_lshlrev_b32_e32 v90, 16, v214
	v_and_b32_e32 v91, 0xffff0000, v214
	v_lshlrev_b32_e32 v92, 16, v215
	v_and_b32_e32 v93, 0xffff0000, v215
	v_mul_f32_e32 v123, v95, v95
	v_fmac_f32_e32 v123, v94, v94
	v_fmac_f32_e32 v123, v96, v96
	v_fmac_f32_e32 v123, v97, v97
	v_fmac_f32_e32 v123, v90, v90
	v_fmac_f32_e32 v123, v91, v91
	v_fmac_f32_e32 v123, v92, v92
	v_fmac_f32_e32 v123, v93, v93
	s_waitcnt vmcnt(15)
	v_lshlrev_b32_e32 v164, 16, v216
	v_and_b32_e32 v165, 0xffff0000, v216
	v_lshlrev_b32_e32 v166, 16, v217
	v_and_b32_e32 v167, 0xffff0000, v217
	v_lshlrev_b32_e32 v168, 16, v218
	v_and_b32_e32 v169, 0xffff0000, v218
	v_lshlrev_b32_e32 v170, 16, v219
	v_and_b32_e32 v171, 0xffff0000, v219
	v_pk_fma_f32 v[86:87], v[148:149], v[86:87], v[164:165]
	v_pk_fma_f32 v[88:89], v[148:149], v[88:89], v[166:167]
	v_pk_fma_f32 v[82:83], v[148:149], v[82:83], v[168:169]
	v_pk_fma_f32 v[84:85], v[148:149], v[84:85], v[170:171]
	v_cvt_pk_bf16_f32 v216, v86, v87
	v_cvt_pk_bf16_f32 v217, v88, v89
	v_cvt_pk_bf16_f32 v218, v82, v83
	v_cvt_pk_bf16_f32 v219, v84, v85
	global_store_dwordx4 v[176:177], v[216:219], off offset:256 nt
	v_lshlrev_b32_e32 v86, 16, v216
	v_and_b32_e32 v87, 0xffff0000, v216
	v_lshlrev_b32_e32 v88, 16, v217
	v_and_b32_e32 v89, 0xffff0000, v217
	v_lshlrev_b32_e32 v82, 16, v218
	v_and_b32_e32 v83, 0xffff0000, v218
	v_lshlrev_b32_e32 v84, 16, v219
	v_and_b32_e32 v85, 0xffff0000, v219
	v_fmac_f32_e32 v123, v86, v86
	v_fmac_f32_e32 v123, v87, v87
	v_fmac_f32_e32 v123, v88, v88
	v_fmac_f32_e32 v123, v89, v89
	v_fmac_f32_e32 v123, v82, v82
	v_fmac_f32_e32 v123, v83, v83
	v_fmac_f32_e32 v123, v84, v84
	v_fmac_f32_e32 v123, v85, v85
	s_waitcnt vmcnt(15)
	v_lshlrev_b32_e32 v164, 16, v220
	v_and_b32_e32 v165, 0xffff0000, v220
	v_lshlrev_b32_e32 v166, 16, v221
	v_and_b32_e32 v167, 0xffff0000, v221
	v_lshlrev_b32_e32 v168, 16, v222
	v_and_b32_e32 v169, 0xffff0000, v222
	v_lshlrev_b32_e32 v170, 16, v223
	v_and_b32_e32 v171, 0xffff0000, v223
	v_pk_fma_f32 v[78:79], v[148:149], v[78:79], v[164:165]
	v_pk_fma_f32 v[80:81], v[148:149], v[80:81], v[166:167]
	v_pk_fma_f32 v[74:75], v[148:149], v[74:75], v[168:169]
	v_pk_fma_f32 v[76:77], v[148:149], v[76:77], v[170:171]
	v_cvt_pk_bf16_f32 v220, v78, v79
	v_cvt_pk_bf16_f32 v221, v80, v81
	v_cvt_pk_bf16_f32 v222, v74, v75
	v_cvt_pk_bf16_f32 v223, v76, v77
	global_store_dwordx4 v[178:179], v[220:223], off nt
	v_lshlrev_b32_e32 v78, 16, v220
	v_and_b32_e32 v79, 0xffff0000, v220
	v_lshlrev_b32_e32 v80, 16, v221
	v_and_b32_e32 v81, 0xffff0000, v221
	v_lshlrev_b32_e32 v74, 16, v222
	v_and_b32_e32 v75, 0xffff0000, v222
	v_lshlrev_b32_e32 v76, 16, v223
	v_and_b32_e32 v77, 0xffff0000, v223
	v_mul_f32_e32 v124, v79, v79
	v_fmac_f32_e32 v124, v78, v78
	v_fmac_f32_e32 v124, v80, v80
	v_fmac_f32_e32 v124, v81, v81
	v_fmac_f32_e32 v124, v74, v74
	v_fmac_f32_e32 v124, v75, v75
	v_fmac_f32_e32 v124, v76, v76
	v_fmac_f32_e32 v124, v77, v77
	s_waitcnt vmcnt(15)
	v_lshlrev_b32_e32 v164, 16, v224
	v_and_b32_e32 v165, 0xffff0000, v224
	v_lshlrev_b32_e32 v166, 16, v225
	v_and_b32_e32 v167, 0xffff0000, v225
	v_lshlrev_b32_e32 v168, 16, v226
	v_and_b32_e32 v169, 0xffff0000, v226
	v_lshlrev_b32_e32 v170, 16, v227
	v_and_b32_e32 v171, 0xffff0000, v227
	v_pk_fma_f32 v[70:71], v[148:149], v[70:71], v[164:165]
	v_pk_fma_f32 v[72:73], v[148:149], v[72:73], v[166:167]
	v_pk_fma_f32 v[66:67], v[148:149], v[66:67], v[168:169]
	v_pk_fma_f32 v[68:69], v[148:149], v[68:69], v[170:171]
	v_cvt_pk_bf16_f32 v224, v70, v71
	v_cvt_pk_bf16_f32 v225, v72, v73
	v_cvt_pk_bf16_f32 v226, v66, v67
	v_cvt_pk_bf16_f32 v227, v68, v69
	global_store_dwordx4 v[178:179], v[224:227], off offset:256 nt
	v_lshlrev_b32_e32 v70, 16, v224
	v_and_b32_e32 v71, 0xffff0000, v224
	v_lshlrev_b32_e32 v72, 16, v225
	v_and_b32_e32 v73, 0xffff0000, v225
	v_lshlrev_b32_e32 v66, 16, v226
	v_and_b32_e32 v67, 0xffff0000, v226
	v_lshlrev_b32_e32 v68, 16, v227
	v_and_b32_e32 v69, 0xffff0000, v227
	v_fmac_f32_e32 v124, v70, v70
	v_fmac_f32_e32 v124, v71, v71
	v_fmac_f32_e32 v124, v72, v72
	v_fmac_f32_e32 v124, v73, v73
	v_fmac_f32_e32 v124, v66, v66
	v_fmac_f32_e32 v124, v67, v67
	v_fmac_f32_e32 v124, v68, v68
	v_fmac_f32_e32 v124, v69, v69
	s_waitcnt vmcnt(15)
	v_lshlrev_b32_e32 v164, 16, v228
	v_and_b32_e32 v165, 0xffff0000, v228
	v_lshlrev_b32_e32 v166, 16, v229
	v_and_b32_e32 v167, 0xffff0000, v229
	v_lshlrev_b32_e32 v168, 16, v230
	v_and_b32_e32 v169, 0xffff0000, v230
	v_lshlrev_b32_e32 v170, 16, v231
	v_and_b32_e32 v171, 0xffff0000, v231
	v_pk_fma_f32 v[62:63], v[148:149], v[62:63], v[164:165]
	v_pk_fma_f32 v[64:65], v[148:149], v[64:65], v[166:167]
	v_pk_fma_f32 v[58:59], v[148:149], v[58:59], v[168:169]
	v_pk_fma_f32 v[60:61], v[148:149], v[60:61], v[170:171]
	v_cvt_pk_bf16_f32 v228, v62, v63
	v_cvt_pk_bf16_f32 v229, v64, v65
	v_cvt_pk_bf16_f32 v230, v58, v59
	v_cvt_pk_bf16_f32 v231, v60, v61
	global_store_dwordx4 v[180:181], v[228:231], off nt
	v_lshlrev_b32_e32 v62, 16, v228
	v_and_b32_e32 v63, 0xffff0000, v228
	v_lshlrev_b32_e32 v64, 16, v229
	v_and_b32_e32 v65, 0xffff0000, v229
	v_lshlrev_b32_e32 v58, 16, v230
	v_and_b32_e32 v59, 0xffff0000, v230
	v_lshlrev_b32_e32 v60, 16, v231
	v_and_b32_e32 v61, 0xffff0000, v231
	v_mul_f32_e32 v125, v63, v63
	v_fmac_f32_e32 v125, v62, v62
	v_fmac_f32_e32 v125, v64, v64
	v_fmac_f32_e32 v125, v65, v65
	v_fmac_f32_e32 v125, v58, v58
	v_fmac_f32_e32 v125, v59, v59
	v_fmac_f32_e32 v125, v60, v60
	v_fmac_f32_e32 v125, v61, v61
	s_waitcnt vmcnt(15)
	v_lshlrev_b32_e32 v164, 16, v232
	v_and_b32_e32 v165, 0xffff0000, v232
	v_lshlrev_b32_e32 v166, 16, v233
	v_and_b32_e32 v167, 0xffff0000, v233
	v_lshlrev_b32_e32 v168, 16, v234
	v_and_b32_e32 v169, 0xffff0000, v234
	v_lshlrev_b32_e32 v170, 16, v235
	v_and_b32_e32 v171, 0xffff0000, v235
	v_pk_fma_f32 v[54:55], v[148:149], v[54:55], v[164:165]
	v_pk_fma_f32 v[56:57], v[148:149], v[56:57], v[166:167]
	v_pk_fma_f32 v[50:51], v[148:149], v[50:51], v[168:169]
	v_pk_fma_f32 v[52:53], v[148:149], v[52:53], v[170:171]
	v_cvt_pk_bf16_f32 v232, v54, v55
	v_cvt_pk_bf16_f32 v233, v56, v57
	v_cvt_pk_bf16_f32 v234, v50, v51
	v_cvt_pk_bf16_f32 v235, v52, v53
	global_store_dwordx4 v[180:181], v[232:235], off offset:256 nt
	v_lshlrev_b32_e32 v54, 16, v232
	v_and_b32_e32 v55, 0xffff0000, v232
	v_lshlrev_b32_e32 v56, 16, v233
	v_and_b32_e32 v57, 0xffff0000, v233
	v_lshlrev_b32_e32 v50, 16, v234
	v_and_b32_e32 v51, 0xffff0000, v234
	v_lshlrev_b32_e32 v52, 16, v235
	v_and_b32_e32 v53, 0xffff0000, v235
	v_fmac_f32_e32 v125, v54, v54
	v_fmac_f32_e32 v125, v55, v55
	v_fmac_f32_e32 v125, v56, v56
	v_fmac_f32_e32 v125, v57, v57
	v_fmac_f32_e32 v125, v50, v50
	v_fmac_f32_e32 v125, v51, v51
	v_fmac_f32_e32 v125, v52, v52
	v_fmac_f32_e32 v125, v53, v53
	s_waitcnt vmcnt(15)
	v_lshlrev_b32_e32 v164, 16, v236
	v_and_b32_e32 v165, 0xffff0000, v236
	v_lshlrev_b32_e32 v166, 16, v237
	v_and_b32_e32 v167, 0xffff0000, v237
	v_lshlrev_b32_e32 v168, 16, v238
	v_and_b32_e32 v169, 0xffff0000, v238
	v_lshlrev_b32_e32 v170, 16, v239
	v_and_b32_e32 v171, 0xffff0000, v239
	v_pk_fma_f32 v[46:47], v[148:149], v[46:47], v[164:165]
	v_pk_fma_f32 v[48:49], v[148:149], v[48:49], v[166:167]
	v_pk_fma_f32 v[42:43], v[148:149], v[42:43], v[168:169]
	v_pk_fma_f32 v[44:45], v[148:149], v[44:45], v[170:171]
	v_cvt_pk_bf16_f32 v236, v46, v47
	v_cvt_pk_bf16_f32 v237, v48, v49
	v_cvt_pk_bf16_f32 v238, v42, v43
	v_cvt_pk_bf16_f32 v239, v44, v45
	global_store_dwordx4 v[182:183], v[236:239], off nt
	v_lshlrev_b32_e32 v46, 16, v236
	v_and_b32_e32 v47, 0xffff0000, v236
	v_lshlrev_b32_e32 v48, 16, v237
	v_and_b32_e32 v49, 0xffff0000, v237
	v_lshlrev_b32_e32 v42, 16, v238
	v_and_b32_e32 v43, 0xffff0000, v238
	v_lshlrev_b32_e32 v44, 16, v239
	v_and_b32_e32 v45, 0xffff0000, v239
	v_mul_f32_e32 v126, v47, v47
	v_fmac_f32_e32 v126, v46, v46
	v_fmac_f32_e32 v126, v48, v48
	v_fmac_f32_e32 v126, v49, v49
	v_fmac_f32_e32 v126, v42, v42
	v_fmac_f32_e32 v126, v43, v43
	v_fmac_f32_e32 v126, v44, v44
	v_fmac_f32_e32 v126, v45, v45
	s_waitcnt vmcnt(15)
	v_lshlrev_b32_e32 v164, 16, v240
	v_and_b32_e32 v165, 0xffff0000, v240
	v_lshlrev_b32_e32 v166, 16, v241
	v_and_b32_e32 v167, 0xffff0000, v241
	v_lshlrev_b32_e32 v168, 16, v242
	v_and_b32_e32 v169, 0xffff0000, v242
	v_lshlrev_b32_e32 v170, 16, v243
	v_and_b32_e32 v171, 0xffff0000, v243
	v_pk_fma_f32 v[38:39], v[148:149], v[38:39], v[164:165]
	v_pk_fma_f32 v[40:41], v[148:149], v[40:41], v[166:167]
	v_pk_fma_f32 v[34:35], v[148:149], v[34:35], v[168:169]
	v_pk_fma_f32 v[36:37], v[148:149], v[36:37], v[170:171]
	v_cvt_pk_bf16_f32 v240, v38, v39
	v_cvt_pk_bf16_f32 v241, v40, v41
	v_cvt_pk_bf16_f32 v242, v34, v35
	v_cvt_pk_bf16_f32 v243, v36, v37
	global_store_dwordx4 v[182:183], v[240:243], off offset:256 nt
	v_lshlrev_b32_e32 v38, 16, v240
	v_and_b32_e32 v39, 0xffff0000, v240
	v_lshlrev_b32_e32 v40, 16, v241
	v_and_b32_e32 v41, 0xffff0000, v241
	v_lshlrev_b32_e32 v34, 16, v242
	v_and_b32_e32 v35, 0xffff0000, v242
	v_lshlrev_b32_e32 v36, 16, v243
	v_and_b32_e32 v37, 0xffff0000, v243
	v_fmac_f32_e32 v126, v38, v38
	v_fmac_f32_e32 v126, v39, v39
	v_fmac_f32_e32 v126, v40, v40
	v_fmac_f32_e32 v126, v41, v41
	v_fmac_f32_e32 v126, v34, v34
	v_fmac_f32_e32 v126, v35, v35
	v_fmac_f32_e32 v126, v36, v36
	v_fmac_f32_e32 v126, v37, v37
	s_waitcnt vmcnt(15)
	v_lshlrev_b32_e32 v164, 16, v244
	v_and_b32_e32 v165, 0xffff0000, v244
	v_lshlrev_b32_e32 v166, 16, v245
	v_and_b32_e32 v167, 0xffff0000, v245
	v_lshlrev_b32_e32 v168, 16, v246
	v_and_b32_e32 v169, 0xffff0000, v246
	v_lshlrev_b32_e32 v170, 16, v247
	v_and_b32_e32 v171, 0xffff0000, v247
	v_pk_fma_f32 v[30:31], v[148:149], v[30:31], v[164:165]
	v_pk_fma_f32 v[32:33], v[148:149], v[32:33], v[166:167]
	v_pk_fma_f32 v[26:27], v[148:149], v[26:27], v[168:169]
	v_pk_fma_f32 v[28:29], v[148:149], v[28:29], v[170:171]
	v_cvt_pk_bf16_f32 v244, v30, v31
	v_cvt_pk_bf16_f32 v245, v32, v33
	v_cvt_pk_bf16_f32 v246, v26, v27
	v_cvt_pk_bf16_f32 v247, v28, v29
	global_store_dwordx4 v[252:253], v[244:247], off nt
	v_lshlrev_b32_e32 v30, 16, v244
	v_and_b32_e32 v31, 0xffff0000, v244
	v_lshlrev_b32_e32 v32, 16, v245
	v_and_b32_e32 v33, 0xffff0000, v245
	v_lshlrev_b32_e32 v26, 16, v246
	v_and_b32_e32 v27, 0xffff0000, v246
	v_lshlrev_b32_e32 v28, 16, v247
	v_and_b32_e32 v29, 0xffff0000, v247
	v_mul_f32_e32 v127, v31, v31
	v_fmac_f32_e32 v127, v30, v30
	v_fmac_f32_e32 v127, v32, v32
	v_fmac_f32_e32 v127, v33, v33
	v_fmac_f32_e32 v127, v26, v26
	v_fmac_f32_e32 v127, v27, v27
	v_fmac_f32_e32 v127, v28, v28
	v_fmac_f32_e32 v127, v29, v29
	s_waitcnt vmcnt(15)
	v_lshlrev_b32_e32 v164, 16, v248
	v_and_b32_e32 v165, 0xffff0000, v248
	v_lshlrev_b32_e32 v166, 16, v249
	v_and_b32_e32 v167, 0xffff0000, v249
	v_lshlrev_b32_e32 v168, 16, v250
	v_and_b32_e32 v169, 0xffff0000, v250
	v_lshlrev_b32_e32 v170, 16, v251
	v_and_b32_e32 v171, 0xffff0000, v251
	v_pk_fma_f32 v[22:23], v[148:149], v[22:23], v[164:165]
	v_pk_fma_f32 v[24:25], v[148:149], v[24:25], v[166:167]
	v_pk_fma_f32 v[18:19], v[148:149], v[18:19], v[168:169]
	v_pk_fma_f32 v[20:21], v[148:149], v[20:21], v[170:171]
	v_cvt_pk_bf16_f32 v248, v22, v23
	v_cvt_pk_bf16_f32 v249, v24, v25
	v_cvt_pk_bf16_f32 v250, v18, v19
	v_cvt_pk_bf16_f32 v251, v20, v21
	global_store_dwordx4 v[252:253], v[248:251], off offset:256 nt
	v_lshlrev_b32_e32 v22, 16, v248
	v_and_b32_e32 v23, 0xffff0000, v248
	v_lshlrev_b32_e32 v24, 16, v249
	v_and_b32_e32 v25, 0xffff0000, v249
	v_lshlrev_b32_e32 v18, 16, v250
	v_and_b32_e32 v19, 0xffff0000, v250
	v_lshlrev_b32_e32 v20, 16, v251
	v_and_b32_e32 v21, 0xffff0000, v251
	v_fmac_f32_e32 v127, v22, v22
	v_fmac_f32_e32 v127, v23, v23
	v_fmac_f32_e32 v127, v24, v24
	v_fmac_f32_e32 v127, v25, v25
	v_fmac_f32_e32 v127, v18, v18
	v_fmac_f32_e32 v127, v19, v19
	v_fmac_f32_e32 v127, v20, v20
	v_fmac_f32_e32 v127, v21, v21
	s_waitcnt vmcnt(13)
	v_lshlrev_b32_e32 v164, 16, v114
	v_and_b32_e32 v165, 0xffff0000, v114
	v_lshlrev_b32_e32 v166, 16, v115
	v_and_b32_e32 v167, 0xffff0000, v115
	v_lshlrev_b32_e32 v168, 16, v116
	v_and_b32_e32 v169, 0xffff0000, v116
	v_lshlrev_b32_e32 v170, 16, v117
	v_and_b32_e32 v171, 0xffff0000, v117
	v_pk_fma_f32 v[14:15], v[148:149], v[14:15], v[164:165]
	v_pk_fma_f32 v[16:17], v[148:149], v[16:17], v[166:167]
	v_pk_fma_f32 v[10:11], v[148:149], v[10:11], v[168:169]
	v_pk_fma_f32 v[12:13], v[148:149], v[12:13], v[170:171]
	v_cvt_pk_bf16_f32 v114, v14, v15
	v_cvt_pk_bf16_f32 v115, v16, v17
	v_cvt_pk_bf16_f32 v116, v10, v11
	v_cvt_pk_bf16_f32 v117, v12, v13
	global_store_dwordx4 v[154:155], v[114:117], off nt
	v_lshlrev_b32_e32 v14, 16, v114
	v_and_b32_e32 v15, 0xffff0000, v114
	v_lshlrev_b32_e32 v16, 16, v115
	v_and_b32_e32 v17, 0xffff0000, v115
	v_lshlrev_b32_e32 v10, 16, v116
	v_and_b32_e32 v11, 0xffff0000, v116
	v_lshlrev_b32_e32 v12, 16, v117
	v_and_b32_e32 v13, 0xffff0000, v117
	v_mul_f32_e32 v128, v15, v15
	v_fmac_f32_e32 v128, v14, v14
	v_fmac_f32_e32 v128, v16, v16
	v_fmac_f32_e32 v128, v17, v17
	v_fmac_f32_e32 v128, v10, v10
	v_fmac_f32_e32 v128, v11, v11
	v_fmac_f32_e32 v128, v12, v12
	v_fmac_f32_e32 v128, v13, v13
	s_waitcnt vmcnt(13)
	v_lshlrev_b32_e32 v164, 16, v118
	v_and_b32_e32 v165, 0xffff0000, v118
	v_lshlrev_b32_e32 v166, 16, v119
	v_and_b32_e32 v167, 0xffff0000, v119
	v_lshlrev_b32_e32 v168, 16, v120
	v_and_b32_e32 v169, 0xffff0000, v120
	v_lshlrev_b32_e32 v170, 16, v121
	v_and_b32_e32 v171, 0xffff0000, v121
	v_pk_fma_f32 v[6:7], v[148:149], v[6:7], v[164:165]
	v_pk_fma_f32 v[8:9], v[148:149], v[8:9], v[166:167]
	v_pk_fma_f32 v[2:3], v[148:149], v[2:3], v[168:169]
	v_pk_fma_f32 v[4:5], v[148:149], v[4:5], v[170:171]
	v_cvt_pk_bf16_f32 v118, v6, v7
	v_cvt_pk_bf16_f32 v119, v8, v9
	v_cvt_pk_bf16_f32 v120, v2, v3
	v_cvt_pk_bf16_f32 v121, v4, v5
	global_store_dwordx4 v[154:155], v[118:121], off offset:256 nt
	v_lshlrev_b32_e32 v6, 16, v118
	v_and_b32_e32 v7, 0xffff0000, v118
	v_lshlrev_b32_e32 v8, 16, v119
	v_and_b32_e32 v9, 0xffff0000, v119
	v_lshlrev_b32_e32 v2, 16, v120
	v_and_b32_e32 v3, 0xffff0000, v120
	v_lshlrev_b32_e32 v4, 16, v121
	v_and_b32_e32 v5, 0xffff0000, v121
	v_fmac_f32_e32 v128, v6, v6
	v_fmac_f32_e32 v128, v7, v7
	v_fmac_f32_e32 v128, v8, v8
	v_fmac_f32_e32 v128, v9, v9
	v_fmac_f32_e32 v128, v2, v2
	v_fmac_f32_e32 v128, v3, v3
	v_fmac_f32_e32 v128, v4, v4
	v_fmac_f32_e32 v128, v5, v5
	v_xor_b32_e32 v106, 16, v189
	v_xor_b32_e32 v107, 32, v189
	v_lshlrev_b32_e32 v106, 2, v106
	v_lshlrev_b32_e32 v107, 2, v107
	ds_bpermute_b32 v98, v106, v172
	ds_bpermute_b32 v99, v106, v122
	ds_bpermute_b32 v100, v106, v123
	ds_bpermute_b32 v101, v106, v124
	ds_bpermute_b32 v102, v106, v125
	ds_bpermute_b32 v103, v106, v126
	ds_bpermute_b32 v104, v106, v127
	ds_bpermute_b32 v105, v106, v128
	s_waitcnt lgkmcnt(0)
	v_add_f32_e32 v172, v172, v98
	v_add_f32_e32 v122, v122, v99
	v_add_f32_e32 v123, v123, v100
	v_add_f32_e32 v124, v124, v101
	v_add_f32_e32 v125, v125, v102
	v_add_f32_e32 v126, v126, v103
	v_add_f32_e32 v127, v127, v104
	v_add_f32_e32 v128, v128, v105
	ds_bpermute_b32 v98, v107, v172
	ds_bpermute_b32 v99, v107, v122
	ds_bpermute_b32 v100, v107, v123
	ds_bpermute_b32 v101, v107, v124
	ds_bpermute_b32 v102, v107, v125
	ds_bpermute_b32 v103, v107, v126
	ds_bpermute_b32 v104, v107, v127
	ds_bpermute_b32 v105, v107, v128
	s_lshl_b32 s0, s33, 2
	s_ashr_i32 s1, s0, 31
	s_lshl_b32 s54, s35, 2
	v_lshlrev_b64 v[108:109], 6, v[156:157]
	v_lshl_add_u64 v[108:109], s[72:73], 0, v[108:109]
	v_lshl_add_u64 v[108:109], s[0:1], 2, v[108:109]
	v_lshl_add_u64 v[108:109], v[108:109], 0, s[54:55]
	s_mov_b64 s[0:1], 0x2000
	v_lshl_add_u64 v[110:111], v[108:109], 0, s[0:1]
	s_waitcnt lgkmcnt(0)
	v_add_f32_e32 v172, v172, v98
	v_add_f32_e32 v122, v122, v99
	v_add_f32_e32 v123, v123, v100
	v_add_f32_e32 v124, v124, v101
	v_add_f32_e32 v125, v125, v102
	v_add_f32_e32 v126, v126, v103
	v_add_f32_e32 v127, v127, v104
	v_add_f32_e32 v128, v128, v105
	s_and_saveexec_b64 s[20:21], s[2:3]
	s_cbranch_execz .Lresid_ss_done
	global_store_dword v[108:109], v172, off
	global_store_dword v[108:109], v122, off offset:1024
	global_store_dword v[108:109], v123, off offset:2048
	global_store_dword v[108:109], v124, off offset:3072
	global_store_dword v[110:111], v125, off
	global_store_dword v[110:111], v126, off offset:1024
	global_store_dword v[110:111], v127, off offset:2048
	global_store_dword v[110:111], v128, off offset:3072
